# grid barrier tail rewritten by hand: per-XCD arrival, last arriver publishes and bumps the top counter, every workgroup polls the top counter directly (no top-generation / per-XCD generation hops), ge
# speedup vs baseline: 1.0846x; 1.0025x over previous
; #define LAS __attribute__((address_space(3)))
; __device__ __forceinline__ unsigned xb_add(unsigned* p, unsigned v) { return __hip_atomic_fetch_add(p, v, __ATOMIC_RELAXED, __HIP_MEMORY_SCOPE_AGENT); }
; __device__ __forceinline__ unsigned xb_xcc_id() { return (unsigned)__builtin_amdgcn_s_getreg((3 << 11) | 20) & 0xFu; }
; __device__ __forceinline__ KP kp_fresh() { KP p = (KP)__builtin_amdgcn_kernarg_segment_ptr(); asm volatile("" : "+s"(p)); return p; }
; __device__ __forceinline__ XcdBarrier xcd_barrier_post(unsigned* bar, volatile LAS unsigned* st) {
;     XcdBarrier b; b.bar = bar; b.x = xb_xcc_id(); b.st = st;
;     if (threadIdx.x == 0) (void)xb_add(&bar[XB_XCNT(b.x)], 1u);
;     return b;
; }
; __global__ void __launch_bounds__(512, 2) hybrid_fwd(Params Pkernarg) {
;     extern __shared__ __attribute__((aligned(16))) unsigned char lds_raw[];
;     LAS unsigned char* lds = (LAS unsigned char*)lds_raw;
;     volatile LAS unsigned* MISC = (volatile LAS unsigned*)(lds + MISC_OFF);
;     if (threadIdx.x < 64) MISC[threadIdx.x] = 0u;
;     __syncthreads();
;     XcdBarrier bar = xcd_barrier_post((unsigned*)(kp_fresh()->ws + WS_CTL) + 4096, MISC + 8);
_Z10hybrid_fwd6Params:
	s_mov_b32 s98, 0
	s_mov_b64 s[94:95], s[0:1]
	v_cmp_gt_u32_e32 vcc, 64, v0
	s_and_saveexec_b64 s[0:1], vcc
	v_lshl_add_u32 v1, v0, 2, 0
	v_add_u32_e32 v1, 0x23f00, v1
	v_mov_b32_e32 v2, 0
	ds_write_b32 v1, v2
	s_or_b64 exec, exec, s[0:1]
	s_mov_b64 s[0:1], s[94:95]
	s_waitcnt lgkmcnt(0)
	s_barrier
	s_load_dwordx2 s[0:1], s[0:1], 0x130
	s_getreg_b32 s3, hwreg(HW_REG_XCC_ID, 0, 4)
	v_cmp_eq_u32_e64 s[6:7], 0, v0
	s_waitcnt lgkmcnt(0)
	s_add_u32 s38, s0, 0x4000
	s_addc_u32 s39, s1, 0
	s_and_b32 s33, s3, 15
	s_lshl_b32 s42, s33, 6
	s_mov_b64 s[4:5], exec
	v_writelane_b32 v244, s6, 0
	s_nop 1
	v_writelane_b32 v244, s7, 1
	s_and_b64 s[6:7], s[4:5], s[6:7]
	s_mov_b64 exec, s[6:7]
	s_cbranch_execz .LBB0_5
	s_mov_b64 s[6:7], exec
	v_mbcnt_lo_u32_b32 v1, s6, 0
	v_mbcnt_hi_u32_b32 v1, s7, v1
	v_cmp_eq_u32_e32 vcc, 0, v1
	s_and_b64 s[8:9], exec, vcc
	s_mov_b64 exec, s[8:9]
	s_cbranch_execz .LBB0_5
	s_lshl_b32 s3, s42, 2
	s_bcnt1_i32_b64 s6, s[6:7]
	v_mov_b32_e32 v1, s3
	v_mov_b32_e32 v2, s6
	global_atomic_add v1, v2, s[38:39] offset:1024

; __device__ __forceinline__ unsigned xb_ld(unsigned* p)              { return __hip_atomic_load(p, __ATOMIC_RELAXED, __HIP_MEMORY_SCOPE_AGENT); }
; __device__ __forceinline__ unsigned xb_add(unsigned* p, unsigned v) { return __hip_atomic_fetch_add(p, v, __ATOMIC_RELAXED, __HIP_MEMORY_SCOPE_AGENT); }
; #define XB_SPIN(cond, bar) do { unsigned _sp = 0; while (cond) { __builtin_amdgcn_s_sleep(1); \
;     if ((++_sp & 255u) == 0u) { if (xb_ld(&(bar)[XB_TMO])) break; if (_sp > XB_SPIN_CAP) { atomicAdd(&(bar)[XB_TMO], 1u); break; } } } } while (0)
; __device__ __forceinline__ void xcd_barrier(const XcdBarrier& b) {
;     ...
;     if (threadIdx.x == 0) {
;         unsigned* bar = b.bar;
;         __builtin_amdgcn_s_waitcnt(0);
;         unsigned nloc = b.st[0], nx = b.st[1];
;         if (nloc == 0u) { xcd_barrier_complete(bar, b.x, nloc, nx); b.st[0] = nloc; b.st[1] = nx; }
;         const unsigned old = xb_add(&bar[XB_XSUB(b.x)], 1u);
;         const unsigned gen = old / nloc;
;         if (old + 1u == (gen + 1u) * nloc) {
;             __builtin_amdgcn_fence(__ATOMIC_RELEASE, "agent");
;             asm volatile("s_waitcnt vmcnt(0)" ::: "memory");
;             const unsigned og = xb_add(&bar[XB_TOP], 1u);
;             const unsigned tg = og / nx;
;             if (og + 1u == (tg + 1u) * nx) xb_add(&bar[XB_TOPGEN], 1u);
;             else XB_SPIN(xb_ld(&bar[XB_TOPGEN]) == tg, bar);
;             __builtin_amdgcn_fence(__ATOMIC_ACQUIRE, "agent");
;             xb_add(&bar[XB_XGEN(b.x)], 1u);
;             asm volatile("s_waitcnt vmcnt(0)" ::: "memory");
;         } else {
;             XB_SPIN(xb_ld(&bar[XB_XGEN(b.x)]) == gen, bar);
;             __builtin_amdgcn_fence(__ATOMIC_ACQUIRE, "agent");
;             asm volatile("s_waitcnt vmcnt(0)" ::: "memory");
;         }
.LBB0_213:
	s_waitcnt lgkmcnt(0)
	v_mov_b32_e32 v1, 0x23f20
	ds_read_b32 v2, v1
	ds_read_b32 v3, v1 offset:4
	v_readlane_b32 s4, v244, 62
	v_readlane_b32 s5, v244, 63
	s_add_u32 s10, s98, 1
	s_mov_b32 s98, s10
	s_waitcnt lgkmcnt(0)
	v_readfirstlane_b32 s8, v2
	v_readfirstlane_b32 s9, v3
	v_mov_b32_e32 v1, 0
	v_mov_b32_e32 v2, 1
	s_nop 1
	global_atomic_add v3, v1, v2, s[4:5] sc0
	s_mul_i32 s8, s8, s10
	s_mul_i32 s9, s9, s10
	v_readlane_b32 s4, v239, 2
	v_readlane_b32 s5, v239, 3
	s_waitcnt vmcnt(0)
	v_readfirstlane_b32 s3, v3
	s_add_u32 s3, s3, 1
	s_cmp_lg_u32 s3, s8
	s_cbranch_scc1 .Lgb56_poll
	buffer_wbl2 sc1
	s_waitcnt vmcnt(0)
	global_atomic_add v1, v2, s[4:5]
.Lgb56_poll:
	s_bitcmp1_b32 s98, 31
	s_cbranch_scc1 .Lgb56_done
	s_mov_b32 s8, 0
.Lgb56_spin:
	global_load_dword v3, v1, s[4:5] sc1
	s_waitcnt vmcnt(0)
	v_readfirstlane_b32 s3, v3
	s_sub_u32 s3, s3, s9
	s_cmp_ge_i32 s3, 0
	s_cbranch_scc1 .Lgb56_done
	s_sleep 1
	s_add_u32 s8, s8, 1
	s_cmp_lt_u32 s8, 0x10000
	s_cbranch_scc1 .Lgb56_spin
	s_bitset1_b32 s98, 31
.Lgb56_done:
	buffer_inv sc1
	s_waitcnt vmcnt(0)

; __device__ __forceinline__ unsigned xb_ld(unsigned* p)              { return __hip_atomic_load(p, __ATOMIC_RELAXED, __HIP_MEMORY_SCOPE_AGENT); }
; __device__ __forceinline__ unsigned xb_add(unsigned* p, unsigned v) { return __hip_atomic_fetch_add(p, v, __ATOMIC_RELAXED, __HIP_MEMORY_SCOPE_AGENT); }
; #define XB_SPIN(cond, bar) do { unsigned _sp = 0; while (cond) { __builtin_amdgcn_s_sleep(1); \
;     if ((++_sp & 255u) == 0u) { if (xb_ld(&(bar)[XB_TMO])) break; if (_sp > XB_SPIN_CAP) { atomicAdd(&(bar)[XB_TMO], 1u); break; } } } } while (0)
; __device__ __forceinline__ void xcd_barrier(const XcdBarrier& b) {
;     ...
;     if (threadIdx.x == 0) {
;         unsigned* bar = b.bar;
;         __builtin_amdgcn_s_waitcnt(0);
;         unsigned nloc = b.st[0], nx = b.st[1];
;         if (nloc == 0u) { xcd_barrier_complete(bar, b.x, nloc, nx); b.st[0] = nloc; b.st[1] = nx; }
;         const unsigned old = xb_add(&bar[XB_XSUB(b.x)], 1u);
;         const unsigned gen = old / nloc;
;         if (old + 1u == (gen + 1u) * nloc) {
;             __builtin_amdgcn_fence(__ATOMIC_RELEASE, "agent");
;             asm volatile("s_waitcnt vmcnt(0)" ::: "memory");
;             const unsigned og = xb_add(&bar[XB_TOP], 1u);
;             const unsigned tg = og / nx;
;             if (og + 1u == (tg + 1u) * nx) xb_add(&bar[XB_TOPGEN], 1u);
;             else XB_SPIN(xb_ld(&bar[XB_TOPGEN]) == tg, bar);
;             __builtin_amdgcn_fence(__ATOMIC_ACQUIRE, "agent");
;             xb_add(&bar[XB_XGEN(b.x)], 1u);
;             asm volatile("s_waitcnt vmcnt(0)" ::: "memory");
;         } else {
;             XB_SPIN(xb_ld(&bar[XB_XGEN(b.x)]) == gen, bar);
;             __builtin_amdgcn_fence(__ATOMIC_ACQUIRE, "agent");
;             asm volatile("s_waitcnt vmcnt(0)" ::: "memory");
;         }
.LBB0_441:
	s_waitcnt lgkmcnt(0)
	v_mov_b32_e32 v1, 0x23f20
	ds_read_b32 v2, v1
	ds_read_b32 v3, v1 offset:4
	v_readlane_b32 s8, v244, 62
	v_readlane_b32 s9, v244, 63
	s_add_u32 s38, s98, 1
	s_mov_b32 s98, s38
	s_waitcnt lgkmcnt(0)
	v_readfirstlane_b32 s10, v2
	v_readfirstlane_b32 s11, v3
	v_mov_b32_e32 v1, 0
	v_mov_b32_e32 v2, 1
	s_nop 1
	global_atomic_add v3, v1, v2, s[8:9] sc0
	s_mul_i32 s10, s10, s38
	s_mul_i32 s11, s11, s38
	v_readlane_b32 s8, v239, 2
	v_readlane_b32 s9, v239, 3
	s_waitcnt vmcnt(0)
	v_readfirstlane_b32 s3, v3
	s_add_u32 s3, s3, 1
	s_cmp_lg_u32 s3, s10
	s_cbranch_scc1 .Lgb2_poll
	buffer_wbl2 sc1
	s_waitcnt vmcnt(0)
	global_atomic_add v1, v2, s[8:9]
.Lgb2_poll:
	s_bitcmp1_b32 s98, 31
	s_cbranch_scc1 .Lgb2_done
	s_mov_b32 s10, 0
.Lgb2_spin:
	global_load_dword v3, v1, s[8:9] sc1
	s_waitcnt vmcnt(0)
	v_readfirstlane_b32 s3, v3
	s_sub_u32 s3, s3, s11
	s_cmp_ge_i32 s3, 0
	s_cbranch_scc1 .Lgb2_done
	s_sleep 1
	s_add_u32 s10, s10, 1
	s_cmp_lt_u32 s10, 0x10000
	s_cbranch_scc1 .Lgb2_spin
	s_bitset1_b32 s98, 31

; __device__ __forceinline__ unsigned xb_ld(unsigned* p)              { return __hip_atomic_load(p, __ATOMIC_RELAXED, __HIP_MEMORY_SCOPE_AGENT); }
; __device__ __forceinline__ unsigned xb_add(unsigned* p, unsigned v) { return __hip_atomic_fetch_add(p, v, __ATOMIC_RELAXED, __HIP_MEMORY_SCOPE_AGENT); }
; #define XB_SPIN(cond, bar) do { unsigned _sp = 0; while (cond) { __builtin_amdgcn_s_sleep(1); \
;     if ((++_sp & 255u) == 0u) { if (xb_ld(&(bar)[XB_TMO])) break; if (_sp > XB_SPIN_CAP) { atomicAdd(&(bar)[XB_TMO], 1u); break; } } } } while (0)
; __device__ __forceinline__ void xcd_barrier(const XcdBarrier& b) {
;     ...
;     if (threadIdx.x == 0) {
;         unsigned* bar = b.bar;
;         __builtin_amdgcn_s_waitcnt(0);
;         unsigned nloc = b.st[0], nx = b.st[1];
;         if (nloc == 0u) { xcd_barrier_complete(bar, b.x, nloc, nx); b.st[0] = nloc; b.st[1] = nx; }
;         const unsigned old = xb_add(&bar[XB_XSUB(b.x)], 1u);
;         const unsigned gen = old / nloc;
;         if (old + 1u == (gen + 1u) * nloc) {
;             __builtin_amdgcn_fence(__ATOMIC_RELEASE, "agent");
;             asm volatile("s_waitcnt vmcnt(0)" ::: "memory");
;             const unsigned og = xb_add(&bar[XB_TOP], 1u);
;             const unsigned tg = og / nx;
;             if (og + 1u == (tg + 1u) * nx) xb_add(&bar[XB_TOPGEN], 1u);
;             else XB_SPIN(xb_ld(&bar[XB_TOPGEN]) == tg, bar);
;             __builtin_amdgcn_fence(__ATOMIC_ACQUIRE, "agent");
;             xb_add(&bar[XB_XGEN(b.x)], 1u);
;             asm volatile("s_waitcnt vmcnt(0)" ::: "memory");
;         } else {
;             XB_SPIN(xb_ld(&bar[XB_XGEN(b.x)]) == gen, bar);
;             __builtin_amdgcn_fence(__ATOMIC_ACQUIRE, "agent");
;             asm volatile("s_waitcnt vmcnt(0)" ::: "memory");
;         }
.LBB0_586:
	s_waitcnt lgkmcnt(0)
	v_mov_b32_e32 v1, 0x23f20
	ds_read_b32 v2, v1
	ds_read_b32 v3, v1 offset:4
	v_readlane_b32 s10, v244, 62
	v_readlane_b32 s11, v244, 63
	s_add_u32 s39, s98, 1
	s_mov_b32 s98, s39
	s_waitcnt lgkmcnt(0)
	v_readfirstlane_b32 s8, v2
	v_readfirstlane_b32 s38, v3
	v_mov_b32_e32 v1, 0
	v_mov_b32_e32 v2, 1
	s_nop 1
	global_atomic_add v3, v1, v2, s[10:11] sc0
	s_mul_i32 s8, s8, s39
	s_mul_i32 s38, s38, s39
	v_readlane_b32 s10, v239, 2
	v_readlane_b32 s11, v239, 3
	s_waitcnt vmcnt(0)
	v_readfirstlane_b32 s3, v3
	s_add_u32 s3, s3, 1
	s_cmp_lg_u32 s3, s8
	s_cbranch_scc1 .Lgb4_poll
	buffer_wbl2 sc1
	s_waitcnt vmcnt(0)
	global_atomic_add v1, v2, s[10:11]

; __device__ __forceinline__ unsigned xb_ld(unsigned* p)              { return __hip_atomic_load(p, __ATOMIC_RELAXED, __HIP_MEMORY_SCOPE_AGENT); }
; __device__ __forceinline__ unsigned xb_add(unsigned* p, unsigned v) { return __hip_atomic_fetch_add(p, v, __ATOMIC_RELAXED, __HIP_MEMORY_SCOPE_AGENT); }
; #define XB_SPIN(cond, bar) do { unsigned _sp = 0; while (cond) { __builtin_amdgcn_s_sleep(1); \
;     if ((++_sp & 255u) == 0u) { if (xb_ld(&(bar)[XB_TMO])) break; if (_sp > XB_SPIN_CAP) { atomicAdd(&(bar)[XB_TMO], 1u); break; } } } } while (0)
; __device__ __forceinline__ void xcd_barrier(const XcdBarrier& b) {
;     ...
;     if (threadIdx.x == 0) {
;         unsigned* bar = b.bar;
;         __builtin_amdgcn_s_waitcnt(0);
;         unsigned nloc = b.st[0], nx = b.st[1];
;         if (nloc == 0u) { xcd_barrier_complete(bar, b.x, nloc, nx); b.st[0] = nloc; b.st[1] = nx; }
;         const unsigned old = xb_add(&bar[XB_XSUB(b.x)], 1u);
;         const unsigned gen = old / nloc;
;         if (old + 1u == (gen + 1u) * nloc) {
;             __builtin_amdgcn_fence(__ATOMIC_RELEASE, "agent");
;             asm volatile("s_waitcnt vmcnt(0)" ::: "memory");
;             const unsigned og = xb_add(&bar[XB_TOP], 1u);
;             const unsigned tg = og / nx;
;             if (og + 1u == (tg + 1u) * nx) xb_add(&bar[XB_TOPGEN], 1u);
;             else XB_SPIN(xb_ld(&bar[XB_TOPGEN]) == tg, bar);
;             __builtin_amdgcn_fence(__ATOMIC_ACQUIRE, "agent");
;             xb_add(&bar[XB_XGEN(b.x)], 1u);
;             asm volatile("s_waitcnt vmcnt(0)" ::: "memory");
;         } else {
;             XB_SPIN(xb_ld(&bar[XB_XGEN(b.x)]) == gen, bar);
;             __builtin_amdgcn_fence(__ATOMIC_ACQUIRE, "agent");
;             asm volatile("s_waitcnt vmcnt(0)" ::: "memory");
;         }
.Lgb4_spin:
	global_load_dword v3, v1, s[10:11] sc1
	s_waitcnt vmcnt(0)
	v_readfirstlane_b32 s3, v3
	s_sub_u32 s3, s3, s38
	s_cmp_ge_i32 s3, 0
	s_cbranch_scc1 .Lgb4_done
	s_sleep 1
	s_add_u32 s8, s8, 1
	s_cmp_lt_u32 s8, 0x10000
	s_cbranch_scc1 .Lgb4_spin
	s_bitset1_b32 s98, 31

; __device__ __forceinline__ unsigned xb_ld(unsigned* p)              { return __hip_atomic_load(p, __ATOMIC_RELAXED, __HIP_MEMORY_SCOPE_AGENT); }
; __device__ __forceinline__ unsigned xb_add(unsigned* p, unsigned v) { return __hip_atomic_fetch_add(p, v, __ATOMIC_RELAXED, __HIP_MEMORY_SCOPE_AGENT); }
; #define XB_SPIN(cond, bar) do { unsigned _sp = 0; while (cond) { __builtin_amdgcn_s_sleep(1); \
;     if ((++_sp & 255u) == 0u) { if (xb_ld(&(bar)[XB_TMO])) break; if (_sp > XB_SPIN_CAP) { atomicAdd(&(bar)[XB_TMO], 1u); break; } } } } while (0)
; __device__ __forceinline__ void xcd_barrier(const XcdBarrier& b) {
;     ...
;     if (threadIdx.x == 0) {
;         unsigned* bar = b.bar;
;         __builtin_amdgcn_s_waitcnt(0);
;         unsigned nloc = b.st[0], nx = b.st[1];
;         if (nloc == 0u) { xcd_barrier_complete(bar, b.x, nloc, nx); b.st[0] = nloc; b.st[1] = nx; }
;         const unsigned old = xb_add(&bar[XB_XSUB(b.x)], 1u);
;         const unsigned gen = old / nloc;
;         if (old + 1u == (gen + 1u) * nloc) {
;             __builtin_amdgcn_fence(__ATOMIC_RELEASE, "agent");
;             asm volatile("s_waitcnt vmcnt(0)" ::: "memory");
;             const unsigned og = xb_add(&bar[XB_TOP], 1u);
;             const unsigned tg = og / nx;
;             if (og + 1u == (tg + 1u) * nx) xb_add(&bar[XB_TOPGEN], 1u);
;             else XB_SPIN(xb_ld(&bar[XB_TOPGEN]) == tg, bar);
;             __builtin_amdgcn_fence(__ATOMIC_ACQUIRE, "agent");
;             xb_add(&bar[XB_XGEN(b.x)], 1u);
;             asm volatile("s_waitcnt vmcnt(0)" ::: "memory");
;         } else {
;             XB_SPIN(xb_ld(&bar[XB_XGEN(b.x)]) == gen, bar);
;             __builtin_amdgcn_fence(__ATOMIC_ACQUIRE, "agent");
;             asm volatile("s_waitcnt vmcnt(0)" ::: "memory");
;         }
.LBB0_677:
	s_waitcnt lgkmcnt(0)
	v_mov_b32_e32 v1, 0x23f20
	ds_read_b32 v2, v1
	ds_read_b32 v3, v1 offset:4
	v_readlane_b32 s8, v244, 62
	v_readlane_b32 s9, v244, 63
	s_add_u32 s41, s98, 1
	s_mov_b32 s98, s41
	s_waitcnt lgkmcnt(0)
	v_readfirstlane_b32 s3, v2
	v_readfirstlane_b32 s40, v3
	v_mov_b32_e32 v1, 0
	v_mov_b32_e32 v2, 1
	s_nop 1
	global_atomic_add v3, v1, v2, s[8:9] sc0
	s_mul_i32 s3, s3, s41
	s_mul_i32 s40, s40, s41
	v_readlane_b32 s8, v239, 2
	v_readlane_b32 s9, v239, 3
	s_waitcnt vmcnt(0)
	v_readfirstlane_b32 s0, v3
	s_add_u32 s0, s0, 1
	s_cmp_lg_u32 s0, s3
	s_cbranch_scc1 .Lgb5_poll
	buffer_wbl2 sc1
	s_waitcnt vmcnt(0)
	global_atomic_add v1, v2, s[8:9]
.Lgb5_poll:
	s_bitcmp1_b32 s98, 31
	s_cbranch_scc1 .Lgb5_done
	s_mov_b32 s3, 0
.Lgb5_spin:
	global_load_dword v3, v1, s[8:9] sc1
	s_waitcnt vmcnt(0)
	v_readfirstlane_b32 s0, v3
	s_sub_u32 s0, s0, s40
	s_cmp_ge_i32 s0, 0
	s_cbranch_scc1 .Lgb5_done
	s_sleep 1
	s_add_u32 s3, s3, 1
	s_cmp_lt_u32 s3, 0x10000
	s_cbranch_scc1 .Lgb5_spin
	s_bitset1_b32 s98, 31

; __device__ __forceinline__ unsigned xb_ld(unsigned* p)              { return __hip_atomic_load(p, __ATOMIC_RELAXED, __HIP_MEMORY_SCOPE_AGENT); }
; __device__ __forceinline__ unsigned xb_add(unsigned* p, unsigned v) { return __hip_atomic_fetch_add(p, v, __ATOMIC_RELAXED, __HIP_MEMORY_SCOPE_AGENT); }
; #define XB_SPIN(cond, bar) do { unsigned _sp = 0; while (cond) { __builtin_amdgcn_s_sleep(1); \
;     if ((++_sp & 255u) == 0u) { if (xb_ld(&(bar)[XB_TMO])) break; if (_sp > XB_SPIN_CAP) { atomicAdd(&(bar)[XB_TMO], 1u); break; } } } } while (0)
; __device__ __forceinline__ void xcd_barrier(const XcdBarrier& b) {
;     ...
;     if (threadIdx.x == 0) {
;         unsigned* bar = b.bar;
;         __builtin_amdgcn_s_waitcnt(0);
;         unsigned nloc = b.st[0], nx = b.st[1];
;         if (nloc == 0u) { xcd_barrier_complete(bar, b.x, nloc, nx); b.st[0] = nloc; b.st[1] = nx; }
;         const unsigned old = xb_add(&bar[XB_XSUB(b.x)], 1u);
;         const unsigned gen = old / nloc;
;         if (old + 1u == (gen + 1u) * nloc) {
;             __builtin_amdgcn_fence(__ATOMIC_RELEASE, "agent");
;             asm volatile("s_waitcnt vmcnt(0)" ::: "memory");
;             const unsigned og = xb_add(&bar[XB_TOP], 1u);
;             const unsigned tg = og / nx;
;             if (og + 1u == (tg + 1u) * nx) xb_add(&bar[XB_TOPGEN], 1u);
;             else XB_SPIN(xb_ld(&bar[XB_TOPGEN]) == tg, bar);
;             __builtin_amdgcn_fence(__ATOMIC_ACQUIRE, "agent");
;             xb_add(&bar[XB_XGEN(b.x)], 1u);
;             asm volatile("s_waitcnt vmcnt(0)" ::: "memory");
;         } else {
;             XB_SPIN(xb_ld(&bar[XB_XGEN(b.x)]) == gen, bar);
;             __builtin_amdgcn_fence(__ATOMIC_ACQUIRE, "agent");
;             asm volatile("s_waitcnt vmcnt(0)" ::: "memory");
;         }
.LBB0_734:
	s_waitcnt lgkmcnt(0)
	v_mov_b32_e32 v2, 0x23f20
	ds_read_b32 v3, v2
	ds_read_b32 v4, v2 offset:4
	v_readlane_b32 s0, v244, 62
	v_readlane_b32 s1, v244, 63
	s_add_u32 s38, s98, 1
	s_mov_b32 s98, s38
	s_waitcnt lgkmcnt(0)
	v_readfirstlane_b32 s8, v3
	v_readfirstlane_b32 s9, v4
	v_mov_b32_e32 v2, 0
	v_mov_b32_e32 v3, 1
	s_nop 1
	global_atomic_add v4, v2, v3, s[0:1] sc0
	s_mul_i32 s8, s8, s38
	s_mul_i32 s9, s9, s38
	v_readlane_b32 s0, v239, 2
	v_readlane_b32 s1, v239, 3
	s_waitcnt vmcnt(0)
	v_readfirstlane_b32 s3, v4
	s_add_u32 s3, s3, 1
	s_cmp_lg_u32 s3, s8
	s_cbranch_scc1 .Lgb6_poll
	buffer_wbl2 sc1
	s_waitcnt vmcnt(0)
	global_atomic_add v2, v3, s[0:1]

; __device__ __forceinline__ unsigned xb_ld(unsigned* p)              { return __hip_atomic_load(p, __ATOMIC_RELAXED, __HIP_MEMORY_SCOPE_AGENT); }
; __device__ __forceinline__ unsigned xb_add(unsigned* p, unsigned v) { return __hip_atomic_fetch_add(p, v, __ATOMIC_RELAXED, __HIP_MEMORY_SCOPE_AGENT); }
; #define XB_SPIN(cond, bar) do { unsigned _sp = 0; while (cond) { __builtin_amdgcn_s_sleep(1); \
;     if ((++_sp & 255u) == 0u) { if (xb_ld(&(bar)[XB_TMO])) break; if (_sp > XB_SPIN_CAP) { atomicAdd(&(bar)[XB_TMO], 1u); break; } } } } while (0)
; __device__ __forceinline__ void xcd_barrier(const XcdBarrier& b) {
;     ...
;     if (threadIdx.x == 0) {
;         unsigned* bar = b.bar;
;         __builtin_amdgcn_s_waitcnt(0);
;         unsigned nloc = b.st[0], nx = b.st[1];
;         if (nloc == 0u) { xcd_barrier_complete(bar, b.x, nloc, nx); b.st[0] = nloc; b.st[1] = nx; }
;         const unsigned old = xb_add(&bar[XB_XSUB(b.x)], 1u);
;         const unsigned gen = old / nloc;
;         if (old + 1u == (gen + 1u) * nloc) {
;             __builtin_amdgcn_fence(__ATOMIC_RELEASE, "agent");
;             asm volatile("s_waitcnt vmcnt(0)" ::: "memory");
;             const unsigned og = xb_add(&bar[XB_TOP], 1u);
;             const unsigned tg = og / nx;
;             if (og + 1u == (tg + 1u) * nx) xb_add(&bar[XB_TOPGEN], 1u);
;             else XB_SPIN(xb_ld(&bar[XB_TOPGEN]) == tg, bar);
;             __builtin_amdgcn_fence(__ATOMIC_ACQUIRE, "agent");
;             xb_add(&bar[XB_XGEN(b.x)], 1u);
;             asm volatile("s_waitcnt vmcnt(0)" ::: "memory");
;         } else {
;             XB_SPIN(xb_ld(&bar[XB_XGEN(b.x)]) == gen, bar);
;             __builtin_amdgcn_fence(__ATOMIC_ACQUIRE, "agent");
;             asm volatile("s_waitcnt vmcnt(0)" ::: "memory");
;         }
.Lgb6_spin:
	global_load_dword v4, v2, s[0:1] sc1
	s_waitcnt vmcnt(0)
	v_readfirstlane_b32 s3, v4
	s_sub_u32 s3, s3, s9
	s_cmp_ge_i32 s3, 0
	s_cbranch_scc1 .Lgb6_done
	s_sleep 1
	s_add_u32 s8, s8, 1
	s_cmp_lt_u32 s8, 0x10000
	s_cbranch_scc1 .Lgb6_spin
	s_bitset1_b32 s98, 31

; __device__ __forceinline__ unsigned xb_ld(unsigned* p)              { return __hip_atomic_load(p, __ATOMIC_RELAXED, __HIP_MEMORY_SCOPE_AGENT); }
; __device__ __forceinline__ unsigned xb_add(unsigned* p, unsigned v) { return __hip_atomic_fetch_add(p, v, __ATOMIC_RELAXED, __HIP_MEMORY_SCOPE_AGENT); }
; #define XB_SPIN(cond, bar) do { unsigned _sp = 0; while (cond) { __builtin_amdgcn_s_sleep(1); \
;     if ((++_sp & 255u) == 0u) { if (xb_ld(&(bar)[XB_TMO])) break; if (_sp > XB_SPIN_CAP) { atomicAdd(&(bar)[XB_TMO], 1u); break; } } } } while (0)
; __device__ __forceinline__ void xcd_barrier(const XcdBarrier& b) {
;     ...
;     if (threadIdx.x == 0) {
;         unsigned* bar = b.bar;
;         __builtin_amdgcn_s_waitcnt(0);
;         unsigned nloc = b.st[0], nx = b.st[1];
;         if (nloc == 0u) { xcd_barrier_complete(bar, b.x, nloc, nx); b.st[0] = nloc; b.st[1] = nx; }
;         const unsigned old = xb_add(&bar[XB_XSUB(b.x)], 1u);
;         const unsigned gen = old / nloc;
;         if (old + 1u == (gen + 1u) * nloc) {
;             __builtin_amdgcn_fence(__ATOMIC_RELEASE, "agent");
;             asm volatile("s_waitcnt vmcnt(0)" ::: "memory");
;             const unsigned og = xb_add(&bar[XB_TOP], 1u);
;             const unsigned tg = og / nx;
;             if (og + 1u == (tg + 1u) * nx) xb_add(&bar[XB_TOPGEN], 1u);
;             else XB_SPIN(xb_ld(&bar[XB_TOPGEN]) == tg, bar);
;             __builtin_amdgcn_fence(__ATOMIC_ACQUIRE, "agent");
;             xb_add(&bar[XB_XGEN(b.x)], 1u);
;             asm volatile("s_waitcnt vmcnt(0)" ::: "memory");
;         } else {
;             XB_SPIN(xb_ld(&bar[XB_XGEN(b.x)]) == gen, bar);
;             __builtin_amdgcn_fence(__ATOMIC_ACQUIRE, "agent");
;             asm volatile("s_waitcnt vmcnt(0)" ::: "memory");
;         }
.LBB0_979:
	s_waitcnt lgkmcnt(0)
	v_mov_b32_e32 v2, 0x23f20
	ds_read_b32 v3, v2
	ds_read_b32 v4, v2 offset:4
	v_readlane_b32 s0, v244, 62
	v_readlane_b32 s1, v244, 63
	s_add_u32 s40, s98, 1
	s_mov_b32 s98, s40
	s_waitcnt lgkmcnt(0)
	v_readfirstlane_b32 s4, v3
	v_readfirstlane_b32 s5, v4
	v_mov_b32_e32 v2, 0
	v_mov_b32_e32 v3, 1
	s_nop 1
	global_atomic_add v4, v2, v3, s[0:1] sc0
	s_mul_i32 s4, s4, s40
	s_mul_i32 s5, s5, s40
	v_readlane_b32 s0, v239, 2
	v_readlane_b32 s1, v239, 3
	s_waitcnt vmcnt(0)
	v_readfirstlane_b32 s3, v4
	s_add_u32 s3, s3, 1
	s_cmp_lg_u32 s3, s4
	s_cbranch_scc1 .Lgb10_poll
	buffer_wbl2 sc1
	s_waitcnt vmcnt(0)
	global_atomic_add v2, v3, s[0:1]
.Lgb10_poll:
	s_bitcmp1_b32 s98, 31
	s_cbranch_scc1 .Lgb10_done
	s_mov_b32 s4, 0
.Lgb10_spin:
	global_load_dword v4, v2, s[0:1] sc1
	s_waitcnt vmcnt(0)
	v_readfirstlane_b32 s3, v4
	s_sub_u32 s3, s3, s5
	s_cmp_ge_i32 s3, 0
	s_cbranch_scc1 .Lgb10_done
	s_sleep 1
	s_add_u32 s4, s4, 1
	s_cmp_lt_u32 s4, 0x10000
	s_cbranch_scc1 .Lgb10_spin
	s_bitset1_b32 s98, 31

; __device__ __forceinline__ unsigned xb_ld(unsigned* p)              { return __hip_atomic_load(p, __ATOMIC_RELAXED, __HIP_MEMORY_SCOPE_AGENT); }
; __device__ __forceinline__ unsigned xb_add(unsigned* p, unsigned v) { return __hip_atomic_fetch_add(p, v, __ATOMIC_RELAXED, __HIP_MEMORY_SCOPE_AGENT); }
; #define XB_SPIN(cond, bar) do { unsigned _sp = 0; while (cond) { __builtin_amdgcn_s_sleep(1); \
;     if ((++_sp & 255u) == 0u) { if (xb_ld(&(bar)[XB_TMO])) break; if (_sp > XB_SPIN_CAP) { atomicAdd(&(bar)[XB_TMO], 1u); break; } } } } while (0)
; __device__ __forceinline__ void xcd_barrier(const XcdBarrier& b) {
;     ...
;     if (threadIdx.x == 0) {
;         unsigned* bar = b.bar;
;         __builtin_amdgcn_s_waitcnt(0);
;         unsigned nloc = b.st[0], nx = b.st[1];
;         if (nloc == 0u) { xcd_barrier_complete(bar, b.x, nloc, nx); b.st[0] = nloc; b.st[1] = nx; }
;         const unsigned old = xb_add(&bar[XB_XSUB(b.x)], 1u);
;         const unsigned gen = old / nloc;
;         if (old + 1u == (gen + 1u) * nloc) {
;             __builtin_amdgcn_fence(__ATOMIC_RELEASE, "agent");
;             asm volatile("s_waitcnt vmcnt(0)" ::: "memory");
;             const unsigned og = xb_add(&bar[XB_TOP], 1u);
;             const unsigned tg = og / nx;
;             if (og + 1u == (tg + 1u) * nx) xb_add(&bar[XB_TOPGEN], 1u);
;             else XB_SPIN(xb_ld(&bar[XB_TOPGEN]) == tg, bar);
;             __builtin_amdgcn_fence(__ATOMIC_ACQUIRE, "agent");
;             xb_add(&bar[XB_XGEN(b.x)], 1u);
;             asm volatile("s_waitcnt vmcnt(0)" ::: "memory");
;         } else {
;             XB_SPIN(xb_ld(&bar[XB_XGEN(b.x)]) == gen, bar);
;             __builtin_amdgcn_fence(__ATOMIC_ACQUIRE, "agent");
;             asm volatile("s_waitcnt vmcnt(0)" ::: "memory");
;         }
.LBB0_3604:
	s_waitcnt lgkmcnt(0)
	v_mov_b32_e32 v1, 0x23f20
	ds_read_b32 v2, v1
	ds_read_b32 v3, v1 offset:4
	v_readlane_b32 s0, v244, 62
	v_readlane_b32 s1, v244, 63
	s_add_u32 s40, s98, 1
	s_mov_b32 s98, s40
	s_waitcnt lgkmcnt(0)
	v_readfirstlane_b32 s4, v2
	v_readfirstlane_b32 s5, v3
	v_mov_b32_e32 v1, 0
	v_mov_b32_e32 v2, 1
	s_nop 1
	global_atomic_add v3, v1, v2, s[0:1] sc0
	s_mul_i32 s4, s4, s40
	s_mul_i32 s5, s5, s40
	v_readlane_b32 s0, v239, 2
	v_readlane_b32 s1, v239, 3
	s_waitcnt vmcnt(0)
	v_readfirstlane_b32 s3, v3
	s_add_u32 s3, s3, 1
	s_cmp_lg_u32 s3, s4
	s_cbranch_scc1 .Lgb45_poll
	buffer_wbl2 sc1
	s_waitcnt vmcnt(0)
	global_atomic_add v1, v2, s[0:1]

; __device__ __forceinline__ unsigned xb_ld(unsigned* p)              { return __hip_atomic_load(p, __ATOMIC_RELAXED, __HIP_MEMORY_SCOPE_AGENT); }
; __device__ __forceinline__ unsigned xb_add(unsigned* p, unsigned v) { return __hip_atomic_fetch_add(p, v, __ATOMIC_RELAXED, __HIP_MEMORY_SCOPE_AGENT); }
; #define XB_SPIN(cond, bar) do { unsigned _sp = 0; while (cond) { __builtin_amdgcn_s_sleep(1); \
;     if ((++_sp & 255u) == 0u) { if (xb_ld(&(bar)[XB_TMO])) break; if (_sp > XB_SPIN_CAP) { atomicAdd(&(bar)[XB_TMO], 1u); break; } } } } while (0)
; __device__ __forceinline__ void xcd_barrier(const XcdBarrier& b) {
;     ...
;     if (threadIdx.x == 0) {
;         unsigned* bar = b.bar;
;         __builtin_amdgcn_s_waitcnt(0);
;         unsigned nloc = b.st[0], nx = b.st[1];
;         if (nloc == 0u) { xcd_barrier_complete(bar, b.x, nloc, nx); b.st[0] = nloc; b.st[1] = nx; }
;         const unsigned old = xb_add(&bar[XB_XSUB(b.x)], 1u);
;         const unsigned gen = old / nloc;
;         if (old + 1u == (gen + 1u) * nloc) {
;             __builtin_amdgcn_fence(__ATOMIC_RELEASE, "agent");
;             asm volatile("s_waitcnt vmcnt(0)" ::: "memory");
;             const unsigned og = xb_add(&bar[XB_TOP], 1u);
;             const unsigned tg = og / nx;
;             if (og + 1u == (tg + 1u) * nx) xb_add(&bar[XB_TOPGEN], 1u);
;             else XB_SPIN(xb_ld(&bar[XB_TOPGEN]) == tg, bar);
;             __builtin_amdgcn_fence(__ATOMIC_ACQUIRE, "agent");
;             xb_add(&bar[XB_XGEN(b.x)], 1u);
;             asm volatile("s_waitcnt vmcnt(0)" ::: "memory");
;         } else {
;             XB_SPIN(xb_ld(&bar[XB_XGEN(b.x)]) == gen, bar);
;             __builtin_amdgcn_fence(__ATOMIC_ACQUIRE, "agent");
;             asm volatile("s_waitcnt vmcnt(0)" ::: "memory");
;         }
.Lgb45_spin:
	global_load_dword v3, v1, s[0:1] sc1
	s_waitcnt vmcnt(0)
	v_readfirstlane_b32 s3, v3
	s_sub_u32 s3, s3, s5
	s_cmp_ge_i32 s3, 0
	s_cbranch_scc1 .Lgb45_done
	s_sleep 1
	s_add_u32 s4, s4, 1
	s_cmp_lt_u32 s4, 0x10000
	s_cbranch_scc1 .Lgb45_spin
	s_bitset1_b32 s98, 31

; __device__ __forceinline__ unsigned xb_ld(unsigned* p)              { return __hip_atomic_load(p, __ATOMIC_RELAXED, __HIP_MEMORY_SCOPE_AGENT); }
; __device__ __forceinline__ unsigned xb_add(unsigned* p, unsigned v) { return __hip_atomic_fetch_add(p, v, __ATOMIC_RELAXED, __HIP_MEMORY_SCOPE_AGENT); }
; #define XB_SPIN(cond, bar) do { unsigned _sp = 0; while (cond) { __builtin_amdgcn_s_sleep(1); \
;     if ((++_sp & 255u) == 0u) { if (xb_ld(&(bar)[XB_TMO])) break; if (_sp > XB_SPIN_CAP) { atomicAdd(&(bar)[XB_TMO], 1u); break; } } } } while (0)
; __device__ __forceinline__ void xcd_barrier(const XcdBarrier& b) {
;     ...
;     if (threadIdx.x == 0) {
;         unsigned* bar = b.bar;
;         __builtin_amdgcn_s_waitcnt(0);
;         unsigned nloc = b.st[0], nx = b.st[1];
;         if (nloc == 0u) { xcd_barrier_complete(bar, b.x, nloc, nx); b.st[0] = nloc; b.st[1] = nx; }
;         const unsigned old = xb_add(&bar[XB_XSUB(b.x)], 1u);
;         const unsigned gen = old / nloc;
;         if (old + 1u == (gen + 1u) * nloc) {
;             __builtin_amdgcn_fence(__ATOMIC_RELEASE, "agent");
;             asm volatile("s_waitcnt vmcnt(0)" ::: "memory");
;             const unsigned og = xb_add(&bar[XB_TOP], 1u);
;             const unsigned tg = og / nx;
;             if (og + 1u == (tg + 1u) * nx) xb_add(&bar[XB_TOPGEN], 1u);
;             else XB_SPIN(xb_ld(&bar[XB_TOPGEN]) == tg, bar);
;             __builtin_amdgcn_fence(__ATOMIC_ACQUIRE, "agent");
;             xb_add(&bar[XB_XGEN(b.x)], 1u);
;             asm volatile("s_waitcnt vmcnt(0)" ::: "memory");
;         } else {
;             XB_SPIN(xb_ld(&bar[XB_XGEN(b.x)]) == gen, bar);
;             __builtin_amdgcn_fence(__ATOMIC_ACQUIRE, "agent");
;             asm volatile("s_waitcnt vmcnt(0)" ::: "memory");
;         }
.LBB0_3726:
	s_waitcnt lgkmcnt(0)
	v_mov_b32_e32 v1, 0x23f20
	ds_read_b32 v2, v1
	ds_read_b32 v3, v1 offset:4
	v_readlane_b32 s4, v244, 62
	v_readlane_b32 s5, v244, 63
	s_add_u32 s38, s98, 1
	s_mov_b32 s98, s38
	s_waitcnt lgkmcnt(0)
	v_readfirstlane_b32 s8, v2
	v_readfirstlane_b32 s9, v3
	v_mov_b32_e32 v1, 0
	v_mov_b32_e32 v2, 1
	s_nop 1
	global_atomic_add v3, v1, v2, s[4:5] sc0
	s_mul_i32 s8, s8, s38
	s_mul_i32 s9, s9, s38
	v_readlane_b32 s4, v239, 2
	v_readlane_b32 s5, v239, 3
	s_waitcnt vmcnt(0)
	v_readfirstlane_b32 s3, v3
	s_add_u32 s3, s3, 1
	s_cmp_lg_u32 s3, s8
	s_cbranch_scc1 .Lgb47_poll
	buffer_wbl2 sc1
	s_waitcnt vmcnt(0)
	global_atomic_add v1, v2, s[4:5]

; __device__ __forceinline__ unsigned xb_ld(unsigned* p)              { return __hip_atomic_load(p, __ATOMIC_RELAXED, __HIP_MEMORY_SCOPE_AGENT); }
; __device__ __forceinline__ unsigned xb_add(unsigned* p, unsigned v) { return __hip_atomic_fetch_add(p, v, __ATOMIC_RELAXED, __HIP_MEMORY_SCOPE_AGENT); }
; #define XB_SPIN(cond, bar) do { unsigned _sp = 0; while (cond) { __builtin_amdgcn_s_sleep(1); \
;     if ((++_sp & 255u) == 0u) { if (xb_ld(&(bar)[XB_TMO])) break; if (_sp > XB_SPIN_CAP) { atomicAdd(&(bar)[XB_TMO], 1u); break; } } } } while (0)
; __device__ __forceinline__ void xcd_barrier(const XcdBarrier& b) {
;     ...
;     if (threadIdx.x == 0) {
;         unsigned* bar = b.bar;
;         __builtin_amdgcn_s_waitcnt(0);
;         unsigned nloc = b.st[0], nx = b.st[1];
;         if (nloc == 0u) { xcd_barrier_complete(bar, b.x, nloc, nx); b.st[0] = nloc; b.st[1] = nx; }
;         const unsigned old = xb_add(&bar[XB_XSUB(b.x)], 1u);
;         const unsigned gen = old / nloc;
;         if (old + 1u == (gen + 1u) * nloc) {
;             __builtin_amdgcn_fence(__ATOMIC_RELEASE, "agent");
;             asm volatile("s_waitcnt vmcnt(0)" ::: "memory");
;             const unsigned og = xb_add(&bar[XB_TOP], 1u);
;             const unsigned tg = og / nx;
;             if (og + 1u == (tg + 1u) * nx) xb_add(&bar[XB_TOPGEN], 1u);
;             else XB_SPIN(xb_ld(&bar[XB_TOPGEN]) == tg, bar);
;             __builtin_amdgcn_fence(__ATOMIC_ACQUIRE, "agent");
;             xb_add(&bar[XB_XGEN(b.x)], 1u);
;             asm volatile("s_waitcnt vmcnt(0)" ::: "memory");
;         } else {
;             XB_SPIN(xb_ld(&bar[XB_XGEN(b.x)]) == gen, bar);
;             __builtin_amdgcn_fence(__ATOMIC_ACQUIRE, "agent");
;             asm volatile("s_waitcnt vmcnt(0)" ::: "memory");
;         }
.LBB0_3790:
	s_waitcnt lgkmcnt(0)
	v_mov_b32_e32 v1, 0x23f20
	ds_read_b32 v2, v1
	ds_read_b32 v3, v1 offset:4
	v_readlane_b32 s4, v244, 62
	v_readlane_b32 s5, v244, 63
	s_add_u32 s40, s98, 1
	s_mov_b32 s98, s40
	s_waitcnt lgkmcnt(0)
	v_readfirstlane_b32 s8, v2
	v_readfirstlane_b32 s9, v3
	v_mov_b32_e32 v1, 0
	v_mov_b32_e32 v2, 1
	s_nop 1
	global_atomic_add v3, v1, v2, s[4:5] sc0
	s_mul_i32 s8, s8, s40
	s_mul_i32 s9, s9, s40
	v_readlane_b32 s4, v239, 2
	v_readlane_b32 s5, v239, 3
	s_waitcnt vmcnt(0)
	v_readfirstlane_b32 s3, v3
	s_add_u32 s3, s3, 1
	s_cmp_lg_u32 s3, s8
	s_cbranch_scc1 .Lgb48_poll
	buffer_wbl2 sc1
	s_waitcnt vmcnt(0)
	global_atomic_add v1, v2, s[4:5]

; __device__ __forceinline__ unsigned xb_ld(unsigned* p)              { return __hip_atomic_load(p, __ATOMIC_RELAXED, __HIP_MEMORY_SCOPE_AGENT); }
; __device__ __forceinline__ unsigned xb_add(unsigned* p, unsigned v) { return __hip_atomic_fetch_add(p, v, __ATOMIC_RELAXED, __HIP_MEMORY_SCOPE_AGENT); }
; #define XB_SPIN(cond, bar) do { unsigned _sp = 0; while (cond) { __builtin_amdgcn_s_sleep(1); \
;     if ((++_sp & 255u) == 0u) { if (xb_ld(&(bar)[XB_TMO])) break; if (_sp > XB_SPIN_CAP) { atomicAdd(&(bar)[XB_TMO], 1u); break; } } } } while (0)
; __device__ __forceinline__ void xcd_barrier(const XcdBarrier& b) {
;     ...
;     if (threadIdx.x == 0) {
;         unsigned* bar = b.bar;
;         __builtin_amdgcn_s_waitcnt(0);
;         unsigned nloc = b.st[0], nx = b.st[1];
;         if (nloc == 0u) { xcd_barrier_complete(bar, b.x, nloc, nx); b.st[0] = nloc; b.st[1] = nx; }
;         const unsigned old = xb_add(&bar[XB_XSUB(b.x)], 1u);
;         const unsigned gen = old / nloc;
;         if (old + 1u == (gen + 1u) * nloc) {
;             __builtin_amdgcn_fence(__ATOMIC_RELEASE, "agent");
;             asm volatile("s_waitcnt vmcnt(0)" ::: "memory");
;             const unsigned og = xb_add(&bar[XB_TOP], 1u);
;             const unsigned tg = og / nx;
;             if (og + 1u == (tg + 1u) * nx) xb_add(&bar[XB_TOPGEN], 1u);
;             else XB_SPIN(xb_ld(&bar[XB_TOPGEN]) == tg, bar);
;             __builtin_amdgcn_fence(__ATOMIC_ACQUIRE, "agent");
;             xb_add(&bar[XB_XGEN(b.x)], 1u);
;             asm volatile("s_waitcnt vmcnt(0)" ::: "memory");
;         } else {
;             XB_SPIN(xb_ld(&bar[XB_XGEN(b.x)]) == gen, bar);
;             __builtin_amdgcn_fence(__ATOMIC_ACQUIRE, "agent");
;             asm volatile("s_waitcnt vmcnt(0)" ::: "memory");
;         }
.LBB0_3913:
	s_waitcnt lgkmcnt(0)
	v_mov_b32_e32 v1, 0x23f20
	ds_read_b32 v2, v1
	ds_read_b32 v3, v1 offset:4
	v_readlane_b32 s2, v244, 62
	v_readlane_b32 s3, v244, 63
	s_add_u32 s9, s98, 1
	s_mov_b32 s98, s9
	s_waitcnt lgkmcnt(0)
	v_readfirstlane_b32 s5, v2
	v_readfirstlane_b32 s8, v3
	v_mov_b32_e32 v1, 0
	v_mov_b32_e32 v2, 1
	s_nop 1
	global_atomic_add v3, v1, v2, s[2:3] sc0
	s_mul_i32 s5, s5, s9
	s_mul_i32 s8, s8, s9
	v_readlane_b32 s2, v239, 2
	v_readlane_b32 s3, v239, 3
	s_waitcnt vmcnt(0)
	v_readfirstlane_b32 s4, v3
	s_add_u32 s4, s4, 1
	s_cmp_lg_u32 s4, s5
	s_cbranch_scc1 .Lgb50_poll
	buffer_wbl2 sc1
	s_waitcnt vmcnt(0)
	global_atomic_add v1, v2, s[2:3]
.Lgb50_poll:
	s_bitcmp1_b32 s98, 31
	s_cbranch_scc1 .Lgb50_done
	s_mov_b32 s5, 0
.Lgb50_spin:
	global_load_dword v3, v1, s[2:3] sc1
	s_waitcnt vmcnt(0)
	v_readfirstlane_b32 s4, v3
	s_sub_u32 s4, s4, s8
	s_cmp_ge_i32 s4, 0
	s_cbranch_scc1 .Lgb50_done
	s_sleep 1
	s_add_u32 s5, s5, 1
	s_cmp_lt_u32 s5, 0x10000
	s_cbranch_scc1 .Lgb50_spin
	s_bitset1_b32 s98, 31

; __device__ __forceinline__ unsigned xb_ld(unsigned* p)              { return __hip_atomic_load(p, __ATOMIC_RELAXED, __HIP_MEMORY_SCOPE_AGENT); }
; __device__ __forceinline__ unsigned xb_add(unsigned* p, unsigned v) { return __hip_atomic_fetch_add(p, v, __ATOMIC_RELAXED, __HIP_MEMORY_SCOPE_AGENT); }
; #define XB_SPIN(cond, bar) do { unsigned _sp = 0; while (cond) { __builtin_amdgcn_s_sleep(1); \
;     if ((++_sp & 255u) == 0u) { if (xb_ld(&(bar)[XB_TMO])) break; if (_sp > XB_SPIN_CAP) { atomicAdd(&(bar)[XB_TMO], 1u); break; } } } } while (0)
; __device__ __forceinline__ void xcd_barrier(const XcdBarrier& b) {
;     ...
;     if (threadIdx.x == 0) {
;         unsigned* bar = b.bar;
;         __builtin_amdgcn_s_waitcnt(0);
;         unsigned nloc = b.st[0], nx = b.st[1];
;         if (nloc == 0u) { xcd_barrier_complete(bar, b.x, nloc, nx); b.st[0] = nloc; b.st[1] = nx; }
;         const unsigned old = xb_add(&bar[XB_XSUB(b.x)], 1u);
;         const unsigned gen = old / nloc;
;         if (old + 1u == (gen + 1u) * nloc) {
;             __builtin_amdgcn_fence(__ATOMIC_RELEASE, "agent");
;             asm volatile("s_waitcnt vmcnt(0)" ::: "memory");
;             const unsigned og = xb_add(&bar[XB_TOP], 1u);
;             const unsigned tg = og / nx;
;             if (og + 1u == (tg + 1u) * nx) xb_add(&bar[XB_TOPGEN], 1u);
;             else XB_SPIN(xb_ld(&bar[XB_TOPGEN]) == tg, bar);
;             __builtin_amdgcn_fence(__ATOMIC_ACQUIRE, "agent");
;             xb_add(&bar[XB_XGEN(b.x)], 1u);
;             asm volatile("s_waitcnt vmcnt(0)" ::: "memory");
;         } else {
;             XB_SPIN(xb_ld(&bar[XB_XGEN(b.x)]) == gen, bar);
;             __builtin_amdgcn_fence(__ATOMIC_ACQUIRE, "agent");
;             asm volatile("s_waitcnt vmcnt(0)" ::: "memory");
;         }
.LBB0_4291:
	s_waitcnt lgkmcnt(0)
	v_mov_b32_e32 v0, 0x23f20
	ds_read_b32 v1, v0
	ds_read_b32 v2, v0 offset:4
	v_readlane_b32 s2, v244, 62
	v_readlane_b32 s3, v244, 63
	s_add_u32 s7, s98, 1
	s_mov_b32 s98, s7
	s_waitcnt lgkmcnt(0)
	v_readfirstlane_b32 s5, v1
	v_readfirstlane_b32 s6, v2
	v_mov_b32_e32 v0, 0
	v_mov_b32_e32 v1, 1
	s_nop 1
	global_atomic_add v2, v0, v1, s[2:3] sc0
	s_mul_i32 s5, s5, s7
	s_mul_i32 s6, s6, s7
	v_readlane_b32 s2, v239, 2
	v_readlane_b32 s3, v239, 3
	s_waitcnt vmcnt(0)
	v_readfirstlane_b32 s4, v2
	s_add_u32 s4, s4, 1
	s_cmp_lg_u32 s4, s5
	s_cbranch_scc1 .Lgb55_poll
	buffer_wbl2 sc1
	s_waitcnt vmcnt(0)
	global_atomic_add v0, v1, s[2:3]

; __device__ __forceinline__ unsigned xb_ld(unsigned* p)              { return __hip_atomic_load(p, __ATOMIC_RELAXED, __HIP_MEMORY_SCOPE_AGENT); }
; __device__ __forceinline__ unsigned xb_add(unsigned* p, unsigned v) { return __hip_atomic_fetch_add(p, v, __ATOMIC_RELAXED, __HIP_MEMORY_SCOPE_AGENT); }
; #define XB_SPIN(cond, bar) do { unsigned _sp = 0; while (cond) { __builtin_amdgcn_s_sleep(1); \
;     if ((++_sp & 255u) == 0u) { if (xb_ld(&(bar)[XB_TMO])) break; if (_sp > XB_SPIN_CAP) { atomicAdd(&(bar)[XB_TMO], 1u); break; } } } } while (0)
; __device__ __forceinline__ void xcd_barrier(const XcdBarrier& b) {
;     ...
;     if (threadIdx.x == 0) {
;         unsigned* bar = b.bar;
;         __builtin_amdgcn_s_waitcnt(0);
;         unsigned nloc = b.st[0], nx = b.st[1];
;         if (nloc == 0u) { xcd_barrier_complete(bar, b.x, nloc, nx); b.st[0] = nloc; b.st[1] = nx; }
;         const unsigned old = xb_add(&bar[XB_XSUB(b.x)], 1u);
;         const unsigned gen = old / nloc;
;         if (old + 1u == (gen + 1u) * nloc) {
;             __builtin_amdgcn_fence(__ATOMIC_RELEASE, "agent");
;             asm volatile("s_waitcnt vmcnt(0)" ::: "memory");
;             const unsigned og = xb_add(&bar[XB_TOP], 1u);
;             const unsigned tg = og / nx;
;             if (og + 1u == (tg + 1u) * nx) xb_add(&bar[XB_TOPGEN], 1u);
;             else XB_SPIN(xb_ld(&bar[XB_TOPGEN]) == tg, bar);
;             __builtin_amdgcn_fence(__ATOMIC_ACQUIRE, "agent");
;             xb_add(&bar[XB_XGEN(b.x)], 1u);
;             asm volatile("s_waitcnt vmcnt(0)" ::: "memory");
;         } else {
;             XB_SPIN(xb_ld(&bar[XB_XGEN(b.x)]) == gen, bar);
;             __builtin_amdgcn_fence(__ATOMIC_ACQUIRE, "agent");
;             asm volatile("s_waitcnt vmcnt(0)" ::: "memory");
;         }
.Lgb55_spin:
	global_load_dword v2, v0, s[2:3] sc1
	s_waitcnt vmcnt(0)
	v_readfirstlane_b32 s4, v2
	s_sub_u32 s4, s4, s6
	s_cmp_ge_i32 s4, 0
	s_cbranch_scc1 .Lgb55_done
	s_sleep 1
	s_add_u32 s5, s5, 1
	s_cmp_lt_u32 s5, 0x10000
	s_cbranch_scc1 .Lgb55_spin
	s_bitset1_b32 s98, 31

; __global__ void __launch_bounds__(512, 2) hybrid_fwd(Params Pkernarg) {
	.amdhsa_kernel _Z10hybrid_fwd6Params
		.amdhsa_group_segment_fixed_size 0
		.amdhsa_private_segment_fixed_size 0
		.amdhsa_kernarg_size 568
		.amdhsa_user_sgpr_count 2
		.amdhsa_user_sgpr_dispatch_ptr 0
		.amdhsa_user_sgpr_queue_ptr 0
		.amdhsa_user_sgpr_kernarg_segment_ptr 1
		.amdhsa_user_sgpr_dispatch_id 0
		.amdhsa_user_sgpr_kernarg_preload_length 0
		.amdhsa_user_sgpr_kernarg_preload_offset 0
		.amdhsa_user_sgpr_private_segment_size 0
		.amdhsa_uses_dynamic_stack 0
		.amdhsa_enable_private_segment 0
		.amdhsa_system_sgpr_workgroup_id_x 1
		.amdhsa_system_sgpr_workgroup_id_y 0
		.amdhsa_system_sgpr_workgroup_id_z 0
		.amdhsa_system_sgpr_workgroup_info 0
		.amdhsa_system_vgpr_workitem_id 0
		.amdhsa_next_free_vgpr 248
		.amdhsa_next_free_sgpr 102
		.amdhsa_accum_offset 248
		.amdhsa_reserve_vcc 1
		.amdhsa_float_round_mode_32 0
		.amdhsa_float_round_mode_16_64 0
		.amdhsa_float_denorm_mode_32 3
		.amdhsa_float_denorm_mode_16_64 3
		.amdhsa_dx10_clamp 1
		.amdhsa_ieee_mode 1
		.amdhsa_fp16_overflow 0
		.amdhsa_tg_split 0
		.amdhsa_exception_fp_ieee_invalid_op 0
		.amdhsa_exception_fp_denorm_src 0
		.amdhsa_exception_fp_ieee_div_zero 0
		.amdhsa_exception_fp_ieee_overflow 0
		.amdhsa_exception_fp_ieee_underflow 0
		.amdhsa_exception_fp_ieee_inexact 0
		.amdhsa_exception_int_div_zero 0
	.end_amdhsa_kernel

; __global__ void __launch_bounds__(512, 2) hybrid_fwd(Params Pkernarg) {
amdhsa.kernels:
  - .agpr_count:     0
    .args:
      - .offset:         0
        .size:           312
        .value_kind:     by_value
      - .offset:         312
        .size:           4
        .value_kind:     hidden_block_count_x
      - .offset:         316
        .size:           4
        .value_kind:     hidden_block_count_y
      - .offset:         320
        .size:           4
        .value_kind:     hidden_block_count_z
      - .offset:         324
        .size:           2
        .value_kind:     hidden_group_size_x
      - .offset:         326
        .size:           2
        .value_kind:     hidden_group_size_y
      - .offset:         328
        .size:           2
        .value_kind:     hidden_group_size_z
      - .offset:         330
        .size:           2
        .value_kind:     hidden_remainder_x
      - .offset:         332
        .size:           2
        .value_kind:     hidden_remainder_y
      - .offset:         334
        .size:           2
        .value_kind:     hidden_remainder_z
      - .offset:         352
        .size:           8
        .value_kind:     hidden_global_offset_x
      - .offset:         360
        .size:           8
        .value_kind:     hidden_global_offset_y
      - .offset:         368
        .size:           8
        .value_kind:     hidden_global_offset_z
      - .offset:         376
        .size:           2
        .value_kind:     hidden_grid_dims
      - .offset:         432
        .size:           4
        .value_kind:     hidden_dynamic_lds_size
    .group_segment_fixed_size: 0
    .kernarg_segment_align: 8
    .kernarg_segment_size: 568
    .language:       OpenCL C
    .language_version:
      - 2
      - 0
    .max_flat_workgroup_size: 512
    .name:           _Z10hybrid_fwd6Params
    .private_segment_fixed_size: 0
    .sgpr_count:     108
    .sgpr_spill_count: 117
    .symbol:         _Z10hybrid_fwd6Params.kd
    .uniform_work_group_size: 1
    .uses_dynamic_stack: false
    .vgpr_count:     248
    .vgpr_spill_count: 0
    .wavefront_size: 64
